# v35 + write-through (sc0 sc1) stores in LN1/LN2 phases so the barrier's L2 writeback has less to flush
# speedup vs baseline: 1.0079x; 1.0010x over previous
; __device__ __forceinline__ int tid_() { int t = threadIdx.x; asm volatile("" : "+v"(t)); return t; }
; DI unsigned pk2(float lo, float hi) { const f32x2 v = {lo, hi}; const bf16x2_t b = __builtin_convertvector(v, bf16x2_t); return __builtin_bit_cast(unsigned, b); }
; DI void ln_phase(float* io, bf16* act, const float* w, const float* b, const bool wr_f32, const bool wr_bf16) {
;     const int tid = tid_(), lane = tid & 63, gw = blockIdx.x * NWAVES + (tid >> 6), ngw = gridDim.x * NWAVES;
;     f32x4 nv[4];
;     if (gw < T) { const f32x4* x0 = (const f32x4*)(io + (size_t)gw * D) + lane;
; #pragma unroll
;         for (int j = 0; j < 4; ++j) nv[j] = x0[64 * j]; }
;     for (int r = gw; r < T; r += ngw) {
;         f32x4* xr = (f32x4*)(io + (size_t)r * D) + lane; f32x4 v[4]; float s = 0.f;
; #pragma unroll
;         for (int j = 0; j < 4; ++j) { v[j] = nv[j]; s += (v[j][0] + v[j][1]) + (v[j][2] + v[j][3]); }
;         if (r + ngw < T) { const f32x4* xn = (const f32x4*)(io + (size_t)(r + ngw) * D) + lane;
; #pragma unroll
;             for (int j = 0; j < 4; ++j) nv[j] = xn[64 * j]; }
;         const float mean = wave_sum(s) * (1.f / D); float s2 = 0.f;
; #pragma unroll
;         for (int j = 0; j < 4; ++j) { v[j] = v[j] - mean; s2 += (v[j][0] * v[j][0] + v[j][1] * v[j][1]) + (v[j][2] * v[j][2] + v[j][3] * v[j][3]); }
;         const float rstd = 1.f / sqrtf(wave_sum(s2) * (1.f / D) + LN_EPS);
;         v2u* o8 = (v2u*)(act + (size_t)r * D) + lane;
; #pragma unroll
;         for (int j = 0; j < 4; ++j) { const f32x4 wv = ((const f32x4*)w)[lane + 64 * j], bv = ((const f32x4*)b)[lane + 64 * j];
;             f32x4 y; y[0] = v[j][0] * rstd * wv[0] + bv[0]; y[1] = v[j][1] * rstd * wv[1] + bv[1]; y[2] = v[j][2] * rstd * wv[2] + bv[2]; y[3] = v[j][3] * rstd * wv[3] + bv[3];
;             if (wr_f32) xr[64 * j] = y; if (wr_bf16) { v2u p; p.x = pk2(y[0], y[1]); p.y = pk2(y[2], y[3]); o8[64 * j] = p; } }
;     }
; }
.LBB0_1112:
	s_or_b64 exec, exec, s[6:7]
	v_add_f32_e32 v33, v12, v13
	v_add_f32_e32 v42, v14, v15
	v_add_f32_e32 v33, v33, v42
	v_add_f32_e32 v42, v8, v9
	v_add_f32_e32 v49, v10, v11
	v_add_f32_e32 v33, 0, v33
	v_add_f32_e32 v42, v42, v49
	v_add_f32_e32 v33, v42, v33
	v_add_f32_e32 v42, v4, v5
	v_add_f32_e32 v49, v6, v7
	v_add_f32_e32 v42, v42, v49
	v_add_f32_e32 v33, v42, v33
	v_add_f32_e32 v42, v0, v1
	v_add_f32_e32 v49, v2, v3
	v_add_f32_e32 v42, v42, v49
	v_add_f32_e32 v33, v42, v33
	s_and_b64 s[0:1], exec, vcc
	s_or_b64 s[2:3], s[0:1], s[2:3]
	s_mov_b32 s0, 0xf800000
	s_nop 1
	v_add_f32_dpp v33, v33, v33 quad_perm:[1,0,3,2] row_mask:0xf bank_mask:0xf
	s_nop 1
	v_add_f32_dpp v33, v33, v33 quad_perm:[2,3,0,1] row_mask:0xf bank_mask:0xf
	s_nop 1
	v_add_f32_dpp v33, v33, v33 row_half_mirror row_mask:0xf bank_mask:0xf
	s_nop 1
	v_add_f32_dpp v33, v33, v33 row_mirror row_mask:0xf bank_mask:0xf
	s_nop 1
	v_add_f32_dpp v33, v33, v33 row_bcast:15 row_mask:0xa bank_mask:0xf
	s_nop 1
	v_add_f32_dpp v33, v33, v33 row_bcast:31 row_mask:0xc bank_mask:0xf
	s_nop 1
	v_readlane_b32 s98, v33, 63
	s_nop 1
	v_mov_b32_e32 v33, s98
	v_fmac_f32_e32 v13, 0xba800000, v33
	v_fmac_f32_e32 v12, 0xba800000, v33
	v_fmac_f32_e32 v15, 0xba800000, v33
	v_fmac_f32_e32 v14, 0xba800000, v33
	v_pk_mul_f32 v[50:51], v[14:15], v[14:15]
	v_pk_mul_f32 v[52:53], v[12:13], v[12:13]
	v_fmac_f32_e32 v9, 0xba800000, v33
	v_pk_mov_b32 v[54:55], v[52:53], v[50:51] op_sel:[1,0]
	v_mov_b32_e32 v53, v51
	v_fmac_f32_e32 v8, 0xba800000, v33
	v_fmac_f32_e32 v11, 0xba800000, v33
	v_fmac_f32_e32 v10, 0xba800000, v33
	v_pk_add_f32 v[50:51], v[54:55], v[52:53]
	v_pk_mul_f32 v[52:53], v[10:11], v[10:11]
	v_pk_mul_f32 v[54:55], v[8:9], v[8:9]
	v_fmac_f32_e32 v4, 0xba800000, v33
	v_pk_mov_b32 v[56:57], v[54:55], v[52:53] op_sel:[1,0]
	v_mov_b32_e32 v55, v53
	v_fmac_f32_e32 v6, 0xba800000, v33
	v_fmac_f32_e32 v5, 0xba800000, v33
	v_mul_f32_e32 v42, v4, v4
	v_pk_add_f32 v[52:53], v[56:57], v[54:55]
	v_fmac_f32_e32 v7, 0xba800000, v33
	v_pk_fma_f32 v[54:55], v[4:5], v[4:5], v[42:43] op_sel_hi:[1,1,0]
	v_mul_f32_e32 v42, v6, v6
	v_pk_add_f32 v[50:51], v[50:51], v[50:51] op_sel_hi:[0,1]
	v_pk_add_f32 v[52:53], v[52:53], v[52:53] op_sel_hi:[0,1]
	v_pk_fma_f32 v[56:57], v[6:7], v[6:7], v[42:43] op_sel_hi:[1,1,0]
	v_fmac_f32_e32 v3, 0xba800000, v33
	v_fmac_f32_e32 v2, 0xba800000, v33
	v_fmac_f32_e32 v1, 0xba800000, v33
	v_fmac_f32_e32 v0, 0xba800000, v33
	v_mul_f32_e32 v54, v0, v0
	v_mul_f32_e32 v56, v1, v1
	v_mul_f32_e32 v50, v2, v2
	v_mul_f32_e32 v52, v3, v3
	v_pk_add_f32 v[54:55], v[54:55], v[56:57]
	v_pk_add_f32 v[50:51], v[50:51], v[52:53]
	s_nop 0
	v_pk_add_f32 v[50:51], v[54:55], v[50:51]
	s_nop 0
	v_add_f32_e32 v33, v50, v51
	s_nop 1
	v_add_f32_dpp v33, v33, v33 quad_perm:[1,0,3,2] row_mask:0xf bank_mask:0xf
	s_nop 1
	v_add_f32_dpp v33, v33, v33 quad_perm:[2,3,0,1] row_mask:0xf bank_mask:0xf
	s_nop 1
	v_add_f32_dpp v33, v33, v33 row_half_mirror row_mask:0xf bank_mask:0xf
	s_nop 1
	v_add_f32_dpp v33, v33, v33 row_mirror row_mask:0xf bank_mask:0xf
	s_nop 1
	v_add_f32_dpp v33, v33, v33 row_bcast:15 row_mask:0xa bank_mask:0xf
	s_nop 1
	v_add_f32_dpp v33, v33, v33 row_bcast:31 row_mask:0xc bank_mask:0xf
	s_nop 1
	v_readlane_b32 s98, v33, 63
	s_nop 1
	v_mov_b32_e32 v33, s98
	v_fmamk_f32 v33, v33, 0x3a800000, v235
	v_cmp_gt_f32_e32 vcc, s0, v33
	v_mul_f32_e32 v42, 0x4f800000, v33
	s_nop 0
	v_cndmask_b32_e32 v33, v33, v42, vcc
	v_sqrt_f32_e32 v42, v33
	s_nop 0
	v_add_u32_e32 v49, -1, v42
	v_fma_f32 v50, -v49, v42, v33
	v_cmp_ge_f32_e64 s[0:1], 0, v50
	v_add_u32_e32 v50, 1, v42
	s_nop 0
	v_cndmask_b32_e64 v49, v42, v49, s[0:1]
	v_fma_f32 v42, -v50, v42, v33
	v_cmp_lt_f32_e64 s[0:1], 0, v42
	s_nop 1
	v_cndmask_b32_e64 v42, v49, v50, s[0:1]
	v_mul_f32_e32 v49, 0x37800000, v42
	v_cndmask_b32_e32 v42, v42, v49, vcc
	v_cmp_class_f32_e32 vcc, v33, v234
	s_nop 1
	v_cndmask_b32_e32 v33, v42, v33, vcc
	v_div_scale_f32 v42, s[0:1], v33, v33, 1.0
	v_rcp_f32_e32 v49, v42
	v_readlane_b32 s0, v254, 15
	v_readlane_b32 s1, v254, 16
	v_fma_f32 v50, -v42, v49, 1.0
	v_fmac_f32_e32 v49, v50, v49
	v_div_scale_f32 v50, vcc, 1.0, v33, 1.0
	v_mul_f32_e32 v51, v50, v49
	v_fma_f32 v52, -v42, v51, v50
	v_fmac_f32_e32 v51, v52, v49
	v_fma_f32 v42, -v42, v51, v50
	v_div_fmas_f32 v42, v42, v49, v51
	v_div_fixup_f32 v42, v42, v33, 1.0
	v_pk_mul_f32 v[12:13], v[12:13], v[42:43] op_sel_hi:[1,0]
	v_pk_mul_f32 v[14:15], v[14:15], v[42:43] op_sel_hi:[1,0]
	v_pk_mul_f32 v[8:9], v[8:9], v[42:43] op_sel_hi:[1,0]
	v_pk_mul_f32 v[10:11], v[10:11], v[42:43] op_sel_hi:[1,0]
	v_pk_mul_f32 v[4:5], v[4:5], v[42:43] op_sel_hi:[1,0]
	v_pk_mul_f32 v[6:7], v[6:7], v[42:43] op_sel_hi:[1,0]
	v_pk_mul_f32 v[0:1], v[0:1], v[42:43] op_sel_hi:[1,0]
	v_pk_mul_f32 v[2:3], v[2:3], v[42:43] op_sel_hi:[1,0]
	v_lshl_add_u64 v[38:39], v[38:39], 0, s[0:1]
	v_readlane_b32 s0, v254, 17
	v_readlane_b32 s1, v254, 18
	v_pk_fma_f32 v[12:13], v[64:65], v[12:13], v[68:69]
	v_pk_fma_f32 v[14:15], v[66:67], v[14:15], v[70:71]
	v_cvt_pk_bf16_f32 v12, v12, v13
	v_cvt_pk_bf16_f32 v13, v14, v15
	global_store_dwordx2 v[40:41], v[12:13], off offset:-1536 sc0 sc1
	s_nop 0
	v_pk_fma_f32 v[8:9], v[72:73], v[8:9], v[76:77]
	v_pk_fma_f32 v[10:11], v[74:75], v[10:11], v[78:79]
	v_cvt_pk_bf16_f32 v8, v8, v9
	v_cvt_pk_bf16_f32 v9, v10, v11
	global_store_dwordx2 v[40:41], v[8:9], off offset:-1024 sc0 sc1
	s_nop 0
	v_pk_fma_f32 v[4:5], v[80:81], v[4:5], v[84:85]
	v_pk_fma_f32 v[6:7], v[82:83], v[6:7], v[86:87]
	v_cvt_pk_bf16_f32 v4, v4, v5
	v_cvt_pk_bf16_f32 v5, v6, v7
	global_store_dwordx2 v[40:41], v[4:5], off offset:-512 sc0 sc1
	s_nop 0
	s_waitcnt vmcnt(3)
	v_mov_b32_e32 v12, v20
	v_mov_b32_e32 v13, v21
	v_mov_b32_e32 v14, v22
	v_mov_b32_e32 v15, v23
	v_pk_fma_f32 v[0:1], v[88:89], v[0:1], v[92:93]
	v_pk_fma_f32 v[2:3], v[90:91], v[2:3], v[94:95]
	v_cvt_pk_bf16_f32 v0, v0, v1
	v_cvt_pk_bf16_f32 v1, v2, v3
	global_store_dwordx2 v[40:41], v[0:1], off sc0 sc1
	v_lshl_add_u64 v[40:41], v[40:41], 0, s[0:1]
	v_mov_b32_e32 v8, v24
	v_mov_b32_e32 v9, v25
	v_mov_b32_e32 v10, v26
	v_mov_b32_e32 v11, v27
	v_mov_b32_e32 v4, v28
	v_mov_b32_e32 v5, v29
	v_mov_b32_e32 v6, v30
	v_mov_b32_e32 v7, v31
	v_mov_b32_e32 v0, v16
	v_mov_b32_e32 v1, v17
	v_mov_b32_e32 v2, v18
	v_mov_b32_e32 v3, v19
	s_andn2_b64 exec, exec, s[2:3]
	s_cbranch_execz .LBB0_1115

; __device__ __forceinline__ int tid_() { int t = threadIdx.x; asm volatile("" : "+v"(t)); return t; }
; DI unsigned pk2(float lo, float hi) { const f32x2 v = {lo, hi}; const bf16x2_t b = __builtin_convertvector(v, bf16x2_t); return __builtin_bit_cast(unsigned, b); }
; DI void ln_phase(float* io, bf16* act, const float* w, const float* b, const bool wr_f32, const bool wr_bf16) {
;     const int tid = tid_(), lane = tid & 63, gw = blockIdx.x * NWAVES + (tid >> 6), ngw = gridDim.x * NWAVES;
;     f32x4 nv[4];
;     if (gw < T) { const f32x4* x0 = (const f32x4*)(io + (size_t)gw * D) + lane;
; #pragma unroll
;         for (int j = 0; j < 4; ++j) nv[j] = x0[64 * j]; }
;     for (int r = gw; r < T; r += ngw) {
;         f32x4* xr = (f32x4*)(io + (size_t)r * D) + lane; f32x4 v[4]; float s = 0.f;
; #pragma unroll
;         for (int j = 0; j < 4; ++j) { v[j] = nv[j]; s += (v[j][0] + v[j][1]) + (v[j][2] + v[j][3]); }
;         if (r + ngw < T) { const f32x4* xn = (const f32x4*)(io + (size_t)(r + ngw) * D) + lane;
; #pragma unroll
;             for (int j = 0; j < 4; ++j) nv[j] = xn[64 * j]; }
;         const float mean = wave_sum(s) * (1.f / D); float s2 = 0.f;
; #pragma unroll
;         for (int j = 0; j < 4; ++j) { v[j] = v[j] - mean; s2 += (v[j][0] * v[j][0] + v[j][1] * v[j][1]) + (v[j][2] * v[j][2] + v[j][3] * v[j][3]); }
;         const float rstd = 1.f / sqrtf(wave_sum(s2) * (1.f / D) + LN_EPS);
;         v2u* o8 = (v2u*)(act + (size_t)r * D) + lane;
; #pragma unroll
;         for (int j = 0; j < 4; ++j) { const f32x4 wv = ((const f32x4*)w)[lane + 64 * j], bv = ((const f32x4*)b)[lane + 64 * j];
;             f32x4 y; y[0] = v[j][0] * rstd * wv[0] + bv[0]; y[1] = v[j][1] * rstd * wv[1] + bv[1]; y[2] = v[j][2] * rstd * wv[2] + bv[2]; y[3] = v[j][3] * rstd * wv[3] + bv[3];
;             if (wr_f32) xr[64 * j] = y; if (wr_bf16) { v2u p; p.x = pk2(y[0], y[1]); p.y = pk2(y[2], y[3]); o8[64 * j] = p; } }
;     }
; }
.LBB0_1316:
	s_or_b64 exec, exec, s[2:3]
	v_add_f32_e32 v33, v28, v29
	v_add_f32_e32 v44, v30, v31
	v_add_f32_e32 v33, v33, v44
	v_add_f32_e32 v44, v8, v9
	v_add_f32_e32 v45, v10, v11
	v_add_f32_e32 v33, 0, v33
	v_add_f32_e32 v44, v44, v45
	v_add_f32_e32 v33, v44, v33
	v_add_f32_e32 v44, v4, v5
	v_add_f32_e32 v45, v6, v7
	v_add_f32_e32 v44, v44, v45
	v_add_f32_e32 v33, v44, v33
	v_add_f32_e32 v44, v0, v1
	v_add_f32_e32 v45, v2, v3
	v_add_f32_e32 v44, v44, v45
	v_add_f32_e32 v33, v44, v33
	s_mov_b32 s2, 0xf800000
	v_readlane_b32 s6, v254, 19
	v_readlane_b32 s7, v254, 20
	v_lshl_add_u64 v[44:45], v[34:35], 0, v[192:193]
	s_nop 1
	v_add_f32_dpp v33, v33, v33 quad_perm:[1,0,3,2] row_mask:0xf bank_mask:0xf
	s_nop 1
	v_add_f32_dpp v33, v33, v33 quad_perm:[2,3,0,1] row_mask:0xf bank_mask:0xf
	s_nop 1
	v_add_f32_dpp v33, v33, v33 row_half_mirror row_mask:0xf bank_mask:0xf
	s_nop 1
	v_add_f32_dpp v33, v33, v33 row_mirror row_mask:0xf bank_mask:0xf
	s_nop 1
	v_add_f32_dpp v33, v33, v33 row_bcast:15 row_mask:0xa bank_mask:0xf
	s_nop 1
	v_add_f32_dpp v33, v33, v33 row_bcast:31 row_mask:0xc bank_mask:0xf
	s_nop 1
	v_readlane_b32 s98, v33, 63
	s_nop 1
	v_mov_b32_e32 v33, s98
	v_fmac_f32_e32 v29, 0xba800000, v33
	v_fmac_f32_e32 v28, 0xba800000, v33
	v_fmac_f32_e32 v31, 0xba800000, v33
	v_fmac_f32_e32 v30, 0xba800000, v33
	v_pk_mul_f32 v[46:47], v[30:31], v[30:31]
	v_pk_mul_f32 v[54:55], v[28:29], v[28:29]
	v_fmac_f32_e32 v11, 0xba800000, v33
	v_pk_mov_b32 v[56:57], v[54:55], v[46:47] op_sel:[1,0]
	v_mov_b32_e32 v55, v47
	v_pk_add_f32 v[46:47], v[56:57], v[54:55]
	v_fmac_f32_e32 v10, 0xba800000, v33
	v_fmac_f32_e32 v9, 0xba800000, v33
	v_fmac_f32_e32 v8, 0xba800000, v33
	v_pk_add_f32 v[46:47], v[46:47], v[46:47] op_sel_hi:[0,1]
	v_pk_mul_f32 v[54:55], v[10:11], v[10:11]
	v_pk_mul_f32 v[56:57], v[8:9], v[8:9]
	v_fmac_f32_e32 v4, 0xba800000, v33
	v_pk_mov_b32 v[58:59], v[56:57], v[54:55] op_sel:[1,0]
	v_mov_b32_e32 v57, v55
	v_fmac_f32_e32 v6, 0xba800000, v33
	v_fmac_f32_e32 v5, 0xba800000, v33
	v_mul_f32_e32 v46, v4, v4
	v_pk_add_f32 v[54:55], v[58:59], v[56:57]
	v_fmac_f32_e32 v7, 0xba800000, v33
	v_pk_fma_f32 v[56:57], v[4:5], v[4:5], v[46:47] op_sel_hi:[1,1,0]
	v_mul_f32_e32 v46, v6, v6
	v_pk_add_f32 v[54:55], v[54:55], v[54:55] op_sel_hi:[0,1]
	v_pk_fma_f32 v[58:59], v[6:7], v[6:7], v[46:47] op_sel_hi:[1,1,0]
	v_fmac_f32_e32 v3, 0xba800000, v33
	v_fmac_f32_e32 v2, 0xba800000, v33
	v_fmac_f32_e32 v1, 0xba800000, v33
	v_fmac_f32_e32 v0, 0xba800000, v33
	v_mul_f32_e32 v56, v0, v0
	v_mul_f32_e32 v58, v1, v1
	v_mul_f32_e32 v46, v2, v2
	v_mul_f32_e32 v54, v3, v3
	v_pk_add_f32 v[56:57], v[56:57], v[58:59]
	v_pk_add_f32 v[46:47], v[46:47], v[54:55]
	s_nop 0
	v_pk_add_f32 v[46:47], v[56:57], v[46:47]
	s_nop 0
	v_add_f32_e32 v33, v46, v47
	s_nop 1
	v_add_f32_dpp v33, v33, v33 quad_perm:[1,0,3,2] row_mask:0xf bank_mask:0xf
	s_nop 1
	v_add_f32_dpp v33, v33, v33 quad_perm:[2,3,0,1] row_mask:0xf bank_mask:0xf
	s_nop 1
	v_add_f32_dpp v33, v33, v33 row_half_mirror row_mask:0xf bank_mask:0xf
	s_nop 1
	v_add_f32_dpp v33, v33, v33 row_mirror row_mask:0xf bank_mask:0xf
	s_nop 1
	v_add_f32_dpp v33, v33, v33 row_bcast:15 row_mask:0xa bank_mask:0xf
	s_nop 1
	v_add_f32_dpp v33, v33, v33 row_bcast:31 row_mask:0xc bank_mask:0xf
	s_nop 1
	v_readlane_b32 s98, v33, 63
	s_nop 1
	v_mov_b32_e32 v33, s98
	v_fmamk_f32 v33, v33, 0x3a800000, v235
	v_cmp_gt_f32_e32 vcc, s2, v33
	v_mul_f32_e32 v46, 0x4f800000, v33
	s_nop 0
	v_cndmask_b32_e32 v33, v33, v46, vcc
	v_sqrt_f32_e32 v46, v33
	s_nop 0
	v_add_u32_e32 v47, -1, v46
	v_fma_f32 v54, -v47, v46, v33
	v_cmp_ge_f32_e64 s[2:3], 0, v54
	v_add_u32_e32 v54, 1, v46
	s_nop 0
	v_cndmask_b32_e64 v47, v46, v47, s[2:3]
	v_fma_f32 v46, -v54, v46, v33
	v_cmp_lt_f32_e64 s[2:3], 0, v46
	s_nop 1
	v_cndmask_b32_e64 v46, v47, v54, s[2:3]
	v_mul_f32_e32 v47, 0x37800000, v46
	v_cndmask_b32_e32 v46, v46, v47, vcc
	v_cmp_class_f32_e32 vcc, v33, v234
	s_nop 1
	v_cndmask_b32_e32 v33, v46, v33, vcc
	v_div_scale_f32 v46, s[2:3], v33, v33, 1.0
	v_rcp_f32_e32 v47, v46
	s_nop 0
	v_fma_f32 v54, -v46, v47, 1.0
	v_fmac_f32_e32 v47, v54, v47
	v_div_scale_f32 v54, vcc, 1.0, v33, 1.0
	v_mul_f32_e32 v55, v54, v47
	v_fma_f32 v56, -v46, v55, v54
	v_fmac_f32_e32 v55, v56, v47
	v_fma_f32 v46, -v46, v55, v54
	v_div_fmas_f32 v46, v46, v47, v55
	v_div_fixup_f32 v46, v46, v33, 1.0
	v_pk_mul_f32 v[28:29], v[28:29], v[46:47] op_sel_hi:[1,0]
	v_pk_mul_f32 v[30:31], v[30:31], v[46:47] op_sel_hi:[1,0]
	v_cndmask_b32_e64 v33, 0, 1, s[6:7]
	v_cmp_ne_u32_e64 s[2:3], 1, v33
	s_andn2_b64 vcc, exec, s[6:7]
	v_pk_fma_f32 v[28:29], v[64:65], v[28:29], v[68:69]
	v_pk_fma_f32 v[30:31], v[66:67], v[30:31], v[70:71]
	global_store_dwordx4 v[44:45], v[28:31], off sc0 sc1
	s_cbranch_vccnz .LBB0_1318
	s_nop 0
	v_cvt_pk_bf16_f32 v28, v28, v29
	v_cvt_pk_bf16_f32 v29, v30, v31
	global_store_dwordx2 v[42:43], v[28:29], off sc0 sc1
.LBB0_1318:
	s_nop 0
	v_mov_b32_e32 v47, v46
	v_pk_mul_f32 v[8:9], v[8:9], v[46:47]
	v_pk_mul_f32 v[10:11], v[10:11], v[46:47]
	s_and_b64 vcc, exec, s[2:3]
	v_pk_fma_f32 v[8:9], v[8:9], v[72:73], v[76:77]
	v_pk_fma_f32 v[10:11], v[10:11], v[74:75], v[78:79]
	global_store_dwordx4 v[44:45], v[8:11], off offset:1024 sc0 sc1
	s_cbranch_vccnz .LBB0_1320
	s_nop 0
	v_cvt_pk_bf16_f32 v8, v8, v9
	v_cvt_pk_bf16_f32 v9, v10, v11
	global_store_dwordx2 v[42:43], v[8:9], off offset:512 sc0 sc1
.LBB0_1320:
	s_nop 0
	v_pk_mul_f32 v[4:5], v[4:5], v[46:47]
	v_pk_mul_f32 v[6:7], v[6:7], v[46:47]
	s_and_b64 vcc, exec, s[2:3]
	v_pk_fma_f32 v[4:5], v[4:5], v[80:81], v[84:85]
	v_pk_fma_f32 v[6:7], v[6:7], v[82:83], v[86:87]
	global_store_dwordx4 v[44:45], v[4:7], off offset:2048 sc0 sc1
	s_cbranch_vccnz .LBB0_1322
	s_nop 0
	v_cvt_pk_bf16_f32 v4, v4, v5
	v_cvt_pk_bf16_f32 v5, v6, v7
	global_store_dwordx2 v[42:43], v[4:5], off offset:1024 sc0 sc1
.LBB0_1322:
	s_nop 0
	v_pk_mul_f32 v[0:1], v[0:1], v[46:47]
	v_pk_mul_f32 v[2:3], v[2:3], v[46:47]
	s_and_b64 vcc, exec, s[2:3]
	v_pk_fma_f32 v[0:1], v[0:1], v[88:89], v[92:93]
	v_pk_fma_f32 v[2:3], v[2:3], v[90:91], v[94:95]
	global_store_dwordx4 v[44:45], v[0:3], off offset:3072 sc0 sc1
	s_cbranch_vccnz .LBB0_1313
	s_nop 0
	v_cvt_pk_bf16_f32 v0, v0, v1
	v_cvt_pk_bf16_f32 v1, v2, v3
	global_store_dwordx2 v[42:43], v[0:1], off offset:1536 sc0 sc1
	s_branch .LBB0_1313
